# K_OUT epilogue f32-residual case (layer 0): hand-written path with residual loads three row groups ahead; compiler ladder removed
# speedup vs baseline: 1.0070x; 1.0021x over previous
;     DI void operator()(const f32x4 (&acc)[2][2][4][2], const Unit& u, int wr, int wc, int fr, int fq, int tid, LAS unsigned char* lds) const {
;     ...
;         case K_OUT: case K_FF2: { EPI_CASE_BEGIN
;             const bool isout = u.kind == K_OUT;
;             const int goff = isout ? 2048 : 5120; const float* src = isout ? xin : out;
;             const float* gn = isout ? g2 : g1n; const float* mn = isout ? mod + 4096 : modn + 1024;
;             float* ssqo = isout ? ssq2 : ssqn; bf16_t* hd = (bf16_t*)(ws + WS_HDN);
;             const bool lastff2 = !isout && (l + 1 == DEPTH);
;             f32x4 gv[2][2], fac[2][2];
; #pragma unroll
;             for (int bj = 0; bj < 2; ++bj)
; #pragma unroll
;                 for (int n = 0; n < 2; ++n) { const int col = u.pn * 256 + lc0 + bj * 128 + n * 4;
;                     gv[bj][n] = *(const f32x4*)(mod + bidx * 6144 + goff + col);
;                     fac[bj][n] = lastff2 ? (f32x4){1.f, 1.f, 1.f, 1.f} : *(const f32x4*)(gn + col) * (*(const f32x4*)(mn + bidx * 6144 + col) + 1.f); }
;             bf16_t* xb = (bf16_t*)out;
;             const bool f32res = isout && l == 0;
; #pragma unroll
;             for (int ai = 0; ai < 2; ++ai)
; #pragma unroll
;                 for (int m = 0; m < 4; ++m) { __builtin_amdgcn_sched_barrier(0);
;                     const size_t ro = (size_t)(row0 + ai * 128 + m * 16) * 1024 + u.pn * 256 + lc0; float sv = 0.f;
; #pragma unroll
;                     for (int bj = 0; bj < 2; ++bj) { const int co = bj * 128;
;                         f32x4 r0, r1;
;                         if (f32res) { r0 = *(const f32x4*)(src + ro + co); r1 = *(const f32x4*)(src + ro + co + 4); }
;                         else { const u32x4 rb = *(const u32x4*)(xb + ro + co); r0 = (f32x4){bf_lo(rb.x), bf_hi(rb.x), bf_lo(rb.y), bf_hi(rb.y)}; r1 = (f32x4){bf_lo(rb.z), bf_hi(rb.z), bf_lo(rb.w), bf_hi(rb.w)}; }
;                         const f32x4 x0 = r0 + gv[bj][0] * acc[ai][bj][m][0], x1 = r1 + gv[bj][1] * acc[ai][bj][m][1];
;                         if (!lastff2) *(u32x4*)(xb + ro + co) = PK8(x0, x1);
;                         sv += ((x0[0] * x0[0] + x0[1] * x0[1]) + (x0[2] * x0[2] + x0[3] * x0[3])) + ((x1[0] * x1[0] + x1[1] * x1[1]) + (x1[2] * x1[2] + x1[3] * x1[3]));
;                         const f32x4 h0 = x0 * fac[bj][0], h1 = x1 * fac[bj][1];
.Lfo32_entry:
	v_add_u32_e32 v178, s54, v0
	v_lshlrev_b32_e32 v179, 10, v178
	v_add3_u32 v179, v179, v146, s44
	v_lshlrev_b32_e32 v148, 2, v179
	v_lshlrev_b32_e32 v179, 1, v179
	s_add_u32 s80, s50, 0x3800000
	s_addc_u32 s81, s51, 0
	global_load_dwordx4 v[180:183], v148, s[76:77]
	global_load_dwordx4 v[184:187], v148, s[76:77] offset:16
	global_load_dwordx4 v[188:191], v148, s[76:77] offset:512
	global_load_dwordx4 v[192:195], v148, s[76:77] offset:528
	s_add_u32 s84, s76, 0x10000
	s_addc_u32 s85, s77, 0
	global_load_dwordx4 v[196:199], v148, s[84:85]
	global_load_dwordx4 v[200:203], v148, s[84:85] offset:16
	global_load_dwordx4 v[204:207], v148, s[84:85] offset:512
	global_load_dwordx4 v[236:239], v148, s[84:85] offset:528
	s_lshl_b32 s2, s38, 2
	s_add_i32 s2, s2, s13
	s_lshl_b32 s2, s2, 2
	v_lshl_add_u32 v178, v178, 6, s2
	s_waitcnt vmcnt(8)
	v_pk_mul_f32 v[126:127], v[126:127], v[138:139]
	v_pk_mul_f32 v[128:129], v[128:129], v[140:141]
	v_pk_mul_f32 v[122:123], v[122:123], v[142:143]
	v_pk_mul_f32 v[124:125], v[124:125], v[144:145]
	v_pk_mul_f32 v[110:111], v[110:111], v[138:139]
	v_pk_mul_f32 v[112:113], v[112:113], v[140:141]
	v_pk_mul_f32 v[106:107], v[106:107], v[142:143]
	v_pk_mul_f32 v[108:109], v[108:109], v[144:145]
	v_pk_mul_f32 v[94:95], v[94:95], v[138:139]
	v_pk_mul_f32 v[96:97], v[96:97], v[140:141]
	v_pk_mul_f32 v[90:91], v[90:91], v[142:143]
	v_pk_mul_f32 v[92:93], v[92:93], v[144:145]
	v_pk_mul_f32 v[78:79], v[78:79], v[138:139]
	v_pk_mul_f32 v[80:81], v[80:81], v[140:141]
	v_pk_mul_f32 v[74:75], v[74:75], v[142:143]
	v_pk_mul_f32 v[76:77], v[76:77], v[144:145]
	v_pk_mul_f32 v[118:119], v[118:119], v[130:131]
	v_pk_mul_f32 v[120:121], v[120:121], v[132:133]
	v_pk_mul_f32 v[114:115], v[114:115], v[134:135]
	v_pk_mul_f32 v[116:117], v[116:117], v[136:137]
	v_pk_mul_f32 v[102:103], v[102:103], v[130:131]
	v_pk_mul_f32 v[104:105], v[104:105], v[132:133]
	v_pk_mul_f32 v[98:99], v[98:99], v[134:135]
	v_pk_mul_f32 v[100:101], v[100:101], v[136:137]
	v_pk_mul_f32 v[86:87], v[86:87], v[130:131]
	v_pk_mul_f32 v[88:89], v[88:89], v[132:133]
	v_pk_mul_f32 v[82:83], v[82:83], v[134:135]
	v_pk_mul_f32 v[84:85], v[84:85], v[136:137]
	v_pk_mul_f32 v[70:71], v[70:71], v[130:131]
	v_pk_mul_f32 v[72:73], v[72:73], v[132:133]
	v_pk_mul_f32 v[66:67], v[66:67], v[134:135]
	v_pk_mul_f32 v[68:69], v[68:69], v[136:137]
	v_pk_mul_f32 v[62:63], v[62:63], v[138:139]
	v_pk_mul_f32 v[64:65], v[64:65], v[140:141]
	v_pk_mul_f32 v[58:59], v[58:59], v[142:143]
	v_pk_mul_f32 v[60:61], v[60:61], v[144:145]
	v_pk_mul_f32 v[46:47], v[46:47], v[138:139]
	v_pk_mul_f32 v[48:49], v[48:49], v[140:141]
	v_pk_mul_f32 v[42:43], v[42:43], v[142:143]
	v_pk_mul_f32 v[44:45], v[44:45], v[144:145]
	v_pk_mul_f32 v[30:31], v[30:31], v[138:139]
	v_pk_mul_f32 v[32:33], v[32:33], v[140:141]
	v_pk_mul_f32 v[26:27], v[26:27], v[142:143]
	v_pk_mul_f32 v[28:29], v[28:29], v[144:145]
	v_pk_mul_f32 v[14:15], v[14:15], v[138:139]
	v_pk_mul_f32 v[16:17], v[16:17], v[140:141]
	v_pk_mul_f32 v[10:11], v[10:11], v[142:143]
	v_pk_mul_f32 v[12:13], v[12:13], v[144:145]
	v_pk_mul_f32 v[54:55], v[54:55], v[130:131]
	v_pk_mul_f32 v[56:57], v[56:57], v[132:133]
	v_pk_mul_f32 v[50:51], v[50:51], v[134:135]
	v_pk_mul_f32 v[52:53], v[52:53], v[136:137]
	v_pk_mul_f32 v[38:39], v[38:39], v[130:131]
	v_pk_mul_f32 v[40:41], v[40:41], v[132:133]
	v_pk_mul_f32 v[34:35], v[34:35], v[134:135]
	v_pk_mul_f32 v[36:37], v[36:37], v[136:137]
	v_pk_mul_f32 v[22:23], v[22:23], v[130:131]
	v_pk_mul_f32 v[24:25], v[24:25], v[132:133]
	v_pk_mul_f32 v[18:19], v[18:19], v[134:135]
	v_pk_mul_f32 v[20:21], v[20:21], v[136:137]
	v_pk_mul_f32 v[6:7], v[6:7], v[130:131]
	v_pk_mul_f32 v[8:9], v[8:9], v[132:133]
	v_pk_mul_f32 v[2:3], v[2:3], v[134:135]
	v_pk_mul_f32 v[4:5], v[4:5], v[136:137]
	s_add_u32 s84, s76, 0x20000
	s_addc_u32 s85, s77, 0
	global_load_dwordx4 v[130:133], v148, s[84:85]
	global_load_dwordx4 v[134:137], v148, s[84:85] offset:16
	global_load_dwordx4 v[138:141], v148, s[84:85] offset:512
	global_load_dwordx4 v[142:145], v148, s[84:85] offset:528
	s_waitcnt vmcnt(8)
	s_add_u32 s44, s48, 0x0
	s_addc_u32 s45, s49, 0
	s_add_u32 s46, s80, 0x0
	s_addc_u32 s47, s81, 0
	v_pk_add_f32 v[126:127], v[126:127], v[180:181]
	v_pk_add_f32 v[128:129], v[128:129], v[182:183]
	v_pk_add_f32 v[122:123], v[122:123], v[184:185]
	v_pk_add_f32 v[124:125], v[124:125], v[186:187]
	v_pk_mul_f32 v[150:151], v[126:127], v[126:127]
	v_pk_fma_f32 v[150:151], v[128:129], v[128:129], v[150:151]
	v_pk_fma_f32 v[150:151], v[122:123], v[122:123], v[150:151]
	v_pk_fma_f32 v[150:151], v[124:125], v[124:125], v[150:151]
	v_cvt_pk_bf16_f32 v180, v126, v127
	v_cvt_pk_bf16_f32 v181, v128, v129
	v_cvt_pk_bf16_f32 v182, v122, v123
	v_cvt_pk_bf16_f32 v183, v124, v125
	global_store_dwordx4 v179, v[180:183], s[44:45]
	v_pk_mul_f32 v[126:127], v[126:127], v[164:165]
	v_pk_mul_f32 v[128:129], v[128:129], v[166:167]
	v_pk_mul_f32 v[122:123], v[122:123], v[162:163]
	v_pk_mul_f32 v[124:125], v[124:125], v[176:177]
	v_cvt_pk_bf16_f32 v240, v126, v127
	v_cvt_pk_bf16_f32 v241, v128, v129
	v_cvt_pk_bf16_f32 v242, v122, v123
	v_cvt_pk_bf16_f32 v243, v124, v125
	global_store_dwordx4 v179, v[240:243], s[46:47]
	v_pk_add_f32 v[118:119], v[118:119], v[188:189]
	v_pk_add_f32 v[120:121], v[120:121], v[190:191]
	v_pk_add_f32 v[114:115], v[114:115], v[192:193]
	v_pk_add_f32 v[116:117], v[116:117], v[194:195]
	v_pk_mul_f32 v[152:153], v[118:119], v[118:119]
	v_pk_fma_f32 v[152:153], v[120:121], v[120:121], v[152:153]
	v_pk_fma_f32 v[152:153], v[114:115], v[114:115], v[152:153]
	v_pk_fma_f32 v[152:153], v[116:117], v[116:117], v[152:153]
	v_cvt_pk_bf16_f32 v188, v118, v119
	v_cvt_pk_bf16_f32 v189, v120, v121
	v_cvt_pk_bf16_f32 v190, v114, v115
	v_cvt_pk_bf16_f32 v191, v116, v117
	global_store_dwordx4 v179, v[188:191], s[44:45] offset:256
	v_pk_mul_f32 v[118:119], v[118:119], v[156:157]
	v_pk_mul_f32 v[120:121], v[120:121], v[158:159]
	v_pk_mul_f32 v[114:115], v[114:115], v[154:155]
	v_pk_mul_f32 v[116:117], v[116:117], v[160:161]
	v_cvt_pk_bf16_f32 v244, v118, v119
	v_cvt_pk_bf16_f32 v245, v120, v121
	v_cvt_pk_bf16_f32 v246, v114, v115
	v_cvt_pk_bf16_f32 v247, v116, v117
	global_store_dwordx4 v179, v[244:247], s[46:47] offset:256
	v_pk_add_f32 v[150:151], v[150:151], v[152:153]
	v_add_f32_e32 v248, v150, v151
	s_add_u32 s84, s76, 0x30000
	s_addc_u32 s85, s77, 0
	global_load_dwordx4 v[180:183], v148, s[84:85]
	global_load_dwordx4 v[184:187], v148, s[84:85] offset:16
	global_load_dwordx4 v[188:191], v148, s[84:85] offset:512
	global_load_dwordx4 v[192:195], v148, s[84:85] offset:528
	s_waitcnt vmcnt(12)
; DI float bf_lo(unsigned u) { return __uint_as_float(u << 16); }
; DI float bf_hi(unsigned u) { return __uint_as_float(u & 0xffff0000u); }
; #define PK8(v0, v1) ((u32x4){pk2((v0)[0], (v0)[1]), pk2((v0)[2], (v0)[3]), pk2((v1)[0], (v1)[1]), pk2((v1)[2], (v1)[3])})
;     DI void operator()(const f32x4 (&acc)[2][2][4][2], const Unit& u, int wr, int wc, int fr, int fq, int tid, LAS unsigned char* lds) const {
;     ...
;             for (int ai = 0; ai < 2; ++ai)
; #pragma unroll
;                 for (int m = 0; m < 4; ++m) { __builtin_amdgcn_sched_barrier(0);
;                     const size_t ro = (size_t)(row0 + ai * 128 + m * 16) * 1024 + u.pn * 256 + lc0; float sv = 0.f;
; #pragma unroll
;                     for (int bj = 0; bj < 2; ++bj) { const int co = bj * 128;
;                         f32x4 r0, r1;
;                         if (f32res) { r0 = *(const f32x4*)(src + ro + co); r1 = *(const f32x4*)(src + ro + co + 4); }
;                         else { const u32x4 rb = *(const u32x4*)(xb + ro + co); r0 = (f32x4){bf_lo(rb.x), bf_hi(rb.x), bf_lo(rb.y), bf_hi(rb.y)}; r1 = (f32x4){bf_lo(rb.z), bf_hi(rb.z), bf_lo(rb.w), bf_hi(rb.w)}; }
;                         const f32x4 x0 = r0 + gv[bj][0] * acc[ai][bj][m][0], x1 = r1 + gv[bj][1] * acc[ai][bj][m][1];
;                         if (!lastff2) *(u32x4*)(xb + ro + co) = PK8(x0, x1);
;                         sv += ((x0[0] * x0[0] + x0[1] * x0[1]) + (x0[2] * x0[2] + x0[3] * x0[3])) + ((x1[0] * x1[0] + x1[1] * x1[1]) + (x1[2] * x1[2] + x1[3] * x1[3]));
;                         const f32x4 h0 = x0 * fac[bj][0], h1 = x1 * fac[bj][1];
;                         *(u32x4*)(hd + ro + co) = PK8(h0, h1); }
;                     sv += __shfl_xor(sv, 16); sv += __shfl_xor(sv, 32);
;                     if (fq == 0) ssqo[(size_t)(row0 + ai * 128 + m * 16) * 16 + u.pn * 4 + wc] = sv; }
	s_add_u32 s44, s48, 0x8000
	s_addc_u32 s45, s49, 0
	s_add_u32 s46, s80, 0x8000
	s_addc_u32 s47, s81, 0
	v_pk_add_f32 v[110:111], v[110:111], v[196:197]
	v_pk_add_f32 v[112:113], v[112:113], v[198:199]
	v_pk_add_f32 v[106:107], v[106:107], v[200:201]
	v_pk_add_f32 v[108:109], v[108:109], v[202:203]
	v_pk_mul_f32 v[150:151], v[110:111], v[110:111]
	v_pk_fma_f32 v[150:151], v[112:113], v[112:113], v[150:151]
	v_pk_fma_f32 v[150:151], v[106:107], v[106:107], v[150:151]
	v_pk_fma_f32 v[150:151], v[108:109], v[108:109], v[150:151]
	v_cvt_pk_bf16_f32 v196, v110, v111
	v_cvt_pk_bf16_f32 v197, v112, v113
	v_cvt_pk_bf16_f32 v198, v106, v107
	v_cvt_pk_bf16_f32 v199, v108, v109
	global_store_dwordx4 v179, v[196:199], s[44:45]
	v_pk_mul_f32 v[110:111], v[110:111], v[164:165]
	v_pk_mul_f32 v[112:113], v[112:113], v[166:167]
	v_pk_mul_f32 v[106:107], v[106:107], v[162:163]
	v_pk_mul_f32 v[108:109], v[108:109], v[176:177]
	v_cvt_pk_bf16_f32 v240, v110, v111
	v_cvt_pk_bf16_f32 v241, v112, v113
	v_cvt_pk_bf16_f32 v242, v106, v107
	v_cvt_pk_bf16_f32 v243, v108, v109
	global_store_dwordx4 v179, v[240:243], s[46:47]
	v_pk_add_f32 v[102:103], v[102:103], v[204:205]
	v_pk_add_f32 v[104:105], v[104:105], v[206:207]
	v_pk_add_f32 v[98:99], v[98:99], v[236:237]
	v_pk_add_f32 v[100:101], v[100:101], v[238:239]
	v_pk_mul_f32 v[152:153], v[102:103], v[102:103]
	v_pk_fma_f32 v[152:153], v[104:105], v[104:105], v[152:153]
	v_pk_fma_f32 v[152:153], v[98:99], v[98:99], v[152:153]
	v_pk_fma_f32 v[152:153], v[100:101], v[100:101], v[152:153]
	v_cvt_pk_bf16_f32 v204, v102, v103
	v_cvt_pk_bf16_f32 v205, v104, v105
	v_cvt_pk_bf16_f32 v206, v98, v99
	v_cvt_pk_bf16_f32 v207, v100, v101
	global_store_dwordx4 v179, v[204:207], s[44:45] offset:256
	v_pk_mul_f32 v[102:103], v[102:103], v[156:157]
	v_pk_mul_f32 v[104:105], v[104:105], v[158:159]
	v_pk_mul_f32 v[98:99], v[98:99], v[154:155]
	v_pk_mul_f32 v[100:101], v[100:101], v[160:161]
	v_cvt_pk_bf16_f32 v244, v102, v103
	v_cvt_pk_bf16_f32 v245, v104, v105
	v_cvt_pk_bf16_f32 v246, v98, v99
	v_cvt_pk_bf16_f32 v247, v100, v101
	global_store_dwordx4 v179, v[244:247], s[46:47] offset:256
	v_pk_add_f32 v[150:151], v[150:151], v[152:153]
	v_add_f32_e32 v249, v150, v151
	s_add_u32 s84, s76, 0x80000
	s_addc_u32 s85, s77, 0
	global_load_dwordx4 v[196:199], v148, s[84:85]
	global_load_dwordx4 v[200:203], v148, s[84:85] offset:16
	global_load_dwordx4 v[204:207], v148, s[84:85] offset:512
	global_load_dwordx4 v[236:239], v148, s[84:85] offset:528
	s_waitcnt vmcnt(16)
	s_add_u32 s44, s48, 0x10000
	s_addc_u32 s45, s49, 0
	s_add_u32 s46, s80, 0x10000
	s_addc_u32 s47, s81, 0
	v_pk_add_f32 v[94:95], v[94:95], v[130:131]
	v_pk_add_f32 v[96:97], v[96:97], v[132:133]
	v_pk_add_f32 v[90:91], v[90:91], v[134:135]
	v_pk_add_f32 v[92:93], v[92:93], v[136:137]
	v_pk_mul_f32 v[150:151], v[94:95], v[94:95]
	v_pk_fma_f32 v[150:151], v[96:97], v[96:97], v[150:151]
	v_pk_fma_f32 v[150:151], v[90:91], v[90:91], v[150:151]
	v_pk_fma_f32 v[150:151], v[92:93], v[92:93], v[150:151]
	v_cvt_pk_bf16_f32 v130, v94, v95
	v_cvt_pk_bf16_f32 v131, v96, v97
	v_cvt_pk_bf16_f32 v132, v90, v91
	v_cvt_pk_bf16_f32 v133, v92, v93
	global_store_dwordx4 v179, v[130:133], s[44:45]
	v_pk_mul_f32 v[94:95], v[94:95], v[164:165]
	v_pk_mul_f32 v[96:97], v[96:97], v[166:167]
	v_pk_mul_f32 v[90:91], v[90:91], v[162:163]
	v_pk_mul_f32 v[92:93], v[92:93], v[176:177]
	v_cvt_pk_bf16_f32 v240, v94, v95
	v_cvt_pk_bf16_f32 v241, v96, v97
	v_cvt_pk_bf16_f32 v242, v90, v91
	v_cvt_pk_bf16_f32 v243, v92, v93
	global_store_dwordx4 v179, v[240:243], s[46:47]
	v_pk_add_f32 v[86:87], v[86:87], v[138:139]
	v_pk_add_f32 v[88:89], v[88:89], v[140:141]
	v_pk_add_f32 v[82:83], v[82:83], v[142:143]
	v_pk_add_f32 v[84:85], v[84:85], v[144:145]
	v_pk_mul_f32 v[152:153], v[86:87], v[86:87]
	v_pk_fma_f32 v[152:153], v[88:89], v[88:89], v[152:153]
	v_pk_fma_f32 v[152:153], v[82:83], v[82:83], v[152:153]
	v_pk_fma_f32 v[152:153], v[84:85], v[84:85], v[152:153]
	v_cvt_pk_bf16_f32 v138, v86, v87
	v_cvt_pk_bf16_f32 v139, v88, v89
	v_cvt_pk_bf16_f32 v140, v82, v83
	v_cvt_pk_bf16_f32 v141, v84, v85
	global_store_dwordx4 v179, v[138:141], s[44:45] offset:256
	v_pk_mul_f32 v[86:87], v[86:87], v[156:157]
	v_pk_mul_f32 v[88:89], v[88:89], v[158:159]
	v_pk_mul_f32 v[82:83], v[82:83], v[154:155]
	v_pk_mul_f32 v[84:85], v[84:85], v[160:161]
	v_cvt_pk_bf16_f32 v244, v86, v87
	v_cvt_pk_bf16_f32 v245, v88, v89
	v_cvt_pk_bf16_f32 v246, v82, v83
	v_cvt_pk_bf16_f32 v247, v84, v85
	global_store_dwordx4 v179, v[244:247], s[46:47] offset:256
	v_pk_add_f32 v[150:151], v[150:151], v[152:153]
	v_add_f32_e32 v250, v150, v151
	s_add_u32 s84, s76, 0x90000
	s_addc_u32 s85, s77, 0
	global_load_dwordx4 v[130:133], v148, s[84:85]
	global_load_dwordx4 v[134:137], v148, s[84:85] offset:16
	global_load_dwordx4 v[138:141], v148, s[84:85] offset:512
	global_load_dwordx4 v[142:145], v148, s[84:85] offset:528
	s_waitcnt vmcnt(16)
; DI float bf_lo(unsigned u) { return __uint_as_float(u << 16); }
; DI float bf_hi(unsigned u) { return __uint_as_float(u & 0xffff0000u); }
; #define PK8(v0, v1) ((u32x4){pk2((v0)[0], (v0)[1]), pk2((v0)[2], (v0)[3]), pk2((v1)[0], (v1)[1]), pk2((v1)[2], (v1)[3])})
;     DI void operator()(const f32x4 (&acc)[2][2][4][2], const Unit& u, int wr, int wc, int fr, int fq, int tid, LAS unsigned char* lds) const {
;     ...
;             for (int ai = 0; ai < 2; ++ai)
; #pragma unroll
;                 for (int m = 0; m < 4; ++m) { __builtin_amdgcn_sched_barrier(0);
;                     const size_t ro = (size_t)(row0 + ai * 128 + m * 16) * 1024 + u.pn * 256 + lc0; float sv = 0.f;
; #pragma unroll
;                     for (int bj = 0; bj < 2; ++bj) { const int co = bj * 128;
;                         f32x4 r0, r1;
;                         if (f32res) { r0 = *(const f32x4*)(src + ro + co); r1 = *(const f32x4*)(src + ro + co + 4); }
;                         else { const u32x4 rb = *(const u32x4*)(xb + ro + co); r0 = (f32x4){bf_lo(rb.x), bf_hi(rb.x), bf_lo(rb.y), bf_hi(rb.y)}; r1 = (f32x4){bf_lo(rb.z), bf_hi(rb.z), bf_lo(rb.w), bf_hi(rb.w)}; }
;                         const f32x4 x0 = r0 + gv[bj][0] * acc[ai][bj][m][0], x1 = r1 + gv[bj][1] * acc[ai][bj][m][1];
;                         if (!lastff2) *(u32x4*)(xb + ro + co) = PK8(x0, x1);
;                         sv += ((x0[0] * x0[0] + x0[1] * x0[1]) + (x0[2] * x0[2] + x0[3] * x0[3])) + ((x1[0] * x1[0] + x1[1] * x1[1]) + (x1[2] * x1[2] + x1[3] * x1[3]));
;                         const f32x4 h0 = x0 * fac[bj][0], h1 = x1 * fac[bj][1];
;                         *(u32x4*)(hd + ro + co) = PK8(h0, h1); }
;                     sv += __shfl_xor(sv, 16); sv += __shfl_xor(sv, 32);
;                     if (fq == 0) ssqo[(size_t)(row0 + ai * 128 + m * 16) * 16 + u.pn * 4 + wc] = sv; }
	s_add_u32 s44, s48, 0x18000
	s_addc_u32 s45, s49, 0
	s_add_u32 s46, s80, 0x18000
	s_addc_u32 s47, s81, 0
	v_pk_add_f32 v[78:79], v[78:79], v[180:181]
	v_pk_add_f32 v[80:81], v[80:81], v[182:183]
	v_pk_add_f32 v[74:75], v[74:75], v[184:185]
	v_pk_add_f32 v[76:77], v[76:77], v[186:187]
	v_pk_mul_f32 v[150:151], v[78:79], v[78:79]
	v_pk_fma_f32 v[150:151], v[80:81], v[80:81], v[150:151]
	v_pk_fma_f32 v[150:151], v[74:75], v[74:75], v[150:151]
	v_pk_fma_f32 v[150:151], v[76:77], v[76:77], v[150:151]
	v_cvt_pk_bf16_f32 v180, v78, v79
	v_cvt_pk_bf16_f32 v181, v80, v81
	v_cvt_pk_bf16_f32 v182, v74, v75
	v_cvt_pk_bf16_f32 v183, v76, v77
	global_store_dwordx4 v179, v[180:183], s[44:45]
	v_pk_mul_f32 v[78:79], v[78:79], v[164:165]
	v_pk_mul_f32 v[80:81], v[80:81], v[166:167]
	v_pk_mul_f32 v[74:75], v[74:75], v[162:163]
	v_pk_mul_f32 v[76:77], v[76:77], v[176:177]
	v_cvt_pk_bf16_f32 v240, v78, v79
	v_cvt_pk_bf16_f32 v241, v80, v81
	v_cvt_pk_bf16_f32 v242, v74, v75
	v_cvt_pk_bf16_f32 v243, v76, v77
	global_store_dwordx4 v179, v[240:243], s[46:47]
	v_pk_add_f32 v[70:71], v[70:71], v[188:189]
	v_pk_add_f32 v[72:73], v[72:73], v[190:191]
	v_pk_add_f32 v[66:67], v[66:67], v[192:193]
	v_pk_add_f32 v[68:69], v[68:69], v[194:195]
	v_pk_mul_f32 v[152:153], v[70:71], v[70:71]
	v_pk_fma_f32 v[152:153], v[72:73], v[72:73], v[152:153]
	v_pk_fma_f32 v[152:153], v[66:67], v[66:67], v[152:153]
	v_pk_fma_f32 v[152:153], v[68:69], v[68:69], v[152:153]
	v_cvt_pk_bf16_f32 v188, v70, v71
	v_cvt_pk_bf16_f32 v189, v72, v73
	v_cvt_pk_bf16_f32 v190, v66, v67
	v_cvt_pk_bf16_f32 v191, v68, v69
	global_store_dwordx4 v179, v[188:191], s[44:45] offset:256
	v_pk_mul_f32 v[70:71], v[70:71], v[156:157]
	v_pk_mul_f32 v[72:73], v[72:73], v[158:159]
	v_pk_mul_f32 v[66:67], v[66:67], v[154:155]
	v_pk_mul_f32 v[68:69], v[68:69], v[160:161]
	v_cvt_pk_bf16_f32 v244, v70, v71
	v_cvt_pk_bf16_f32 v245, v72, v73
	v_cvt_pk_bf16_f32 v246, v66, v67
	v_cvt_pk_bf16_f32 v247, v68, v69
	global_store_dwordx4 v179, v[244:247], s[46:47] offset:256
	v_pk_add_f32 v[150:151], v[150:151], v[152:153]
	v_add_f32_e32 v251, v150, v151
	s_add_u32 s84, s76, 0xa0000
	s_addc_u32 s85, s77, 0
	global_load_dwordx4 v[180:183], v148, s[84:85]
	global_load_dwordx4 v[184:187], v148, s[84:85] offset:16
	global_load_dwordx4 v[188:191], v148, s[84:85] offset:512
	global_load_dwordx4 v[192:195], v148, s[84:85] offset:528
	s_waitcnt vmcnt(16)
	s_add_u32 s44, s48, 0x40000
	s_addc_u32 s45, s49, 0
	s_add_u32 s46, s80, 0x40000
	s_addc_u32 s47, s81, 0
	v_pk_add_f32 v[62:63], v[62:63], v[196:197]
	v_pk_add_f32 v[64:65], v[64:65], v[198:199]
	v_pk_add_f32 v[58:59], v[58:59], v[200:201]
	v_pk_add_f32 v[60:61], v[60:61], v[202:203]
	v_pk_mul_f32 v[150:151], v[62:63], v[62:63]
	v_pk_fma_f32 v[150:151], v[64:65], v[64:65], v[150:151]
	v_pk_fma_f32 v[150:151], v[58:59], v[58:59], v[150:151]
	v_pk_fma_f32 v[150:151], v[60:61], v[60:61], v[150:151]
	v_cvt_pk_bf16_f32 v196, v62, v63
	v_cvt_pk_bf16_f32 v197, v64, v65
	v_cvt_pk_bf16_f32 v198, v58, v59
	v_cvt_pk_bf16_f32 v199, v60, v61
	global_store_dwordx4 v179, v[196:199], s[44:45]
	v_pk_mul_f32 v[62:63], v[62:63], v[164:165]
	v_pk_mul_f32 v[64:65], v[64:65], v[166:167]
	v_pk_mul_f32 v[58:59], v[58:59], v[162:163]
	v_pk_mul_f32 v[60:61], v[60:61], v[176:177]
	v_cvt_pk_bf16_f32 v240, v62, v63
	v_cvt_pk_bf16_f32 v241, v64, v65
	v_cvt_pk_bf16_f32 v242, v58, v59
	v_cvt_pk_bf16_f32 v243, v60, v61
	global_store_dwordx4 v179, v[240:243], s[46:47]
	v_pk_add_f32 v[54:55], v[54:55], v[204:205]
	v_pk_add_f32 v[56:57], v[56:57], v[206:207]
	v_pk_add_f32 v[50:51], v[50:51], v[236:237]
	v_pk_add_f32 v[52:53], v[52:53], v[238:239]
	v_pk_mul_f32 v[152:153], v[54:55], v[54:55]
	v_pk_fma_f32 v[152:153], v[56:57], v[56:57], v[152:153]
	v_pk_fma_f32 v[152:153], v[50:51], v[50:51], v[152:153]
	v_pk_fma_f32 v[152:153], v[52:53], v[52:53], v[152:153]
	v_cvt_pk_bf16_f32 v204, v54, v55
	v_cvt_pk_bf16_f32 v205, v56, v57
	v_cvt_pk_bf16_f32 v206, v50, v51
	v_cvt_pk_bf16_f32 v207, v52, v53
	global_store_dwordx4 v179, v[204:207], s[44:45] offset:256
	v_pk_mul_f32 v[54:55], v[54:55], v[156:157]
	v_pk_mul_f32 v[56:57], v[56:57], v[158:159]
	v_pk_mul_f32 v[50:51], v[50:51], v[154:155]
	v_pk_mul_f32 v[52:53], v[52:53], v[160:161]
	v_cvt_pk_bf16_f32 v244, v54, v55
	v_cvt_pk_bf16_f32 v245, v56, v57
	v_cvt_pk_bf16_f32 v246, v50, v51
	v_cvt_pk_bf16_f32 v247, v52, v53
	global_store_dwordx4 v179, v[244:247], s[46:47] offset:256
	v_pk_add_f32 v[150:151], v[150:151], v[152:153]
	v_add_f32_e32 v208, v150, v151
	s_add_u32 s84, s76, 0xb0000
	s_addc_u32 s85, s77, 0
	global_load_dwordx4 v[196:199], v148, s[84:85]
	global_load_dwordx4 v[200:203], v148, s[84:85] offset:16
	global_load_dwordx4 v[204:207], v148, s[84:85] offset:512
	global_load_dwordx4 v[236:239], v148, s[84:85] offset:528
	s_waitcnt vmcnt(16)
; DI float bf_lo(unsigned u) { return __uint_as_float(u << 16); }
; DI float bf_hi(unsigned u) { return __uint_as_float(u & 0xffff0000u); }
; #define PK8(v0, v1) ((u32x4){pk2((v0)[0], (v0)[1]), pk2((v0)[2], (v0)[3]), pk2((v1)[0], (v1)[1]), pk2((v1)[2], (v1)[3])})
;     DI void operator()(const f32x4 (&acc)[2][2][4][2], const Unit& u, int wr, int wc, int fr, int fq, int tid, LAS unsigned char* lds) const {
;     ...
; #pragma unroll
;             for (int ai = 0; ai < 2; ++ai)
; #pragma unroll
;                 for (int m = 0; m < 4; ++m) { __builtin_amdgcn_sched_barrier(0);
;                     const size_t ro = (size_t)(row0 + ai * 128 + m * 16) * 1024 + u.pn * 256 + lc0; float sv = 0.f;
; #pragma unroll
;                     for (int bj = 0; bj < 2; ++bj) { const int co = bj * 128;
;                         f32x4 r0, r1;
;                         if (f32res) { r0 = *(const f32x4*)(src + ro + co); r1 = *(const f32x4*)(src + ro + co + 4); }
;                         else { const u32x4 rb = *(const u32x4*)(xb + ro + co); r0 = (f32x4){bf_lo(rb.x), bf_hi(rb.x), bf_lo(rb.y), bf_hi(rb.y)}; r1 = (f32x4){bf_lo(rb.z), bf_hi(rb.z), bf_lo(rb.w), bf_hi(rb.w)}; }
;                         const f32x4 x0 = r0 + gv[bj][0] * acc[ai][bj][m][0], x1 = r1 + gv[bj][1] * acc[ai][bj][m][1];
;                         if (!lastff2) *(u32x4*)(xb + ro + co) = PK8(x0, x1);
;                         sv += ((x0[0] * x0[0] + x0[1] * x0[1]) + (x0[2] * x0[2] + x0[3] * x0[3])) + ((x1[0] * x1[0] + x1[1] * x1[1]) + (x1[2] * x1[2] + x1[3] * x1[3]));
;                         const f32x4 h0 = x0 * fac[bj][0], h1 = x1 * fac[bj][1];
;                         *(u32x4*)(hd + ro + co) = PK8(h0, h1); }
;                     sv += __shfl_xor(sv, 16); sv += __shfl_xor(sv, 32);
;                     if (fq == 0) ssqo[(size_t)(row0 + ai * 128 + m * 16) * 16 + u.pn * 4 + wc] = sv; }
	s_add_u32 s44, s48, 0x48000
	s_addc_u32 s45, s49, 0
	s_add_u32 s46, s80, 0x48000
	s_addc_u32 s47, s81, 0
	v_pk_add_f32 v[46:47], v[46:47], v[130:131]
	v_pk_add_f32 v[48:49], v[48:49], v[132:133]
	v_pk_add_f32 v[42:43], v[42:43], v[134:135]
	v_pk_add_f32 v[44:45], v[44:45], v[136:137]
	v_pk_mul_f32 v[150:151], v[46:47], v[46:47]
	v_pk_fma_f32 v[150:151], v[48:49], v[48:49], v[150:151]
	v_pk_fma_f32 v[150:151], v[42:43], v[42:43], v[150:151]
	v_pk_fma_f32 v[150:151], v[44:45], v[44:45], v[150:151]
	v_cvt_pk_bf16_f32 v130, v46, v47
	v_cvt_pk_bf16_f32 v131, v48, v49
	v_cvt_pk_bf16_f32 v132, v42, v43
	v_cvt_pk_bf16_f32 v133, v44, v45
	global_store_dwordx4 v179, v[130:133], s[44:45]
	v_pk_mul_f32 v[46:47], v[46:47], v[164:165]
	v_pk_mul_f32 v[48:49], v[48:49], v[166:167]
	v_pk_mul_f32 v[42:43], v[42:43], v[162:163]
	v_pk_mul_f32 v[44:45], v[44:45], v[176:177]
	v_cvt_pk_bf16_f32 v240, v46, v47
	v_cvt_pk_bf16_f32 v241, v48, v49
	v_cvt_pk_bf16_f32 v242, v42, v43
	v_cvt_pk_bf16_f32 v243, v44, v45
	global_store_dwordx4 v179, v[240:243], s[46:47]
	v_pk_add_f32 v[38:39], v[38:39], v[138:139]
	v_pk_add_f32 v[40:41], v[40:41], v[140:141]
	v_pk_add_f32 v[34:35], v[34:35], v[142:143]
	v_pk_add_f32 v[36:37], v[36:37], v[144:145]
	v_pk_mul_f32 v[152:153], v[38:39], v[38:39]
	v_pk_fma_f32 v[152:153], v[40:41], v[40:41], v[152:153]
	v_pk_fma_f32 v[152:153], v[34:35], v[34:35], v[152:153]
	v_pk_fma_f32 v[152:153], v[36:37], v[36:37], v[152:153]
	v_cvt_pk_bf16_f32 v138, v38, v39
	v_cvt_pk_bf16_f32 v139, v40, v41
	v_cvt_pk_bf16_f32 v140, v34, v35
	v_cvt_pk_bf16_f32 v141, v36, v37
	global_store_dwordx4 v179, v[138:141], s[44:45] offset:256
	v_pk_mul_f32 v[38:39], v[38:39], v[156:157]
	v_pk_mul_f32 v[40:41], v[40:41], v[158:159]
	v_pk_mul_f32 v[34:35], v[34:35], v[154:155]
	v_pk_mul_f32 v[36:37], v[36:37], v[160:161]
	v_cvt_pk_bf16_f32 v244, v38, v39
	v_cvt_pk_bf16_f32 v245, v40, v41
	v_cvt_pk_bf16_f32 v246, v34, v35
	v_cvt_pk_bf16_f32 v247, v36, v37
	global_store_dwordx4 v179, v[244:247], s[46:47] offset:256
	v_pk_add_f32 v[150:151], v[150:151], v[152:153]
	v_add_f32_e32 v209, v150, v151
	s_waitcnt vmcnt(12)
	s_add_u32 s44, s48, 0x50000
	s_addc_u32 s45, s49, 0
	s_add_u32 s46, s80, 0x50000
	s_addc_u32 s47, s81, 0
	v_pk_add_f32 v[30:31], v[30:31], v[180:181]
	v_pk_add_f32 v[32:33], v[32:33], v[182:183]
	v_pk_add_f32 v[26:27], v[26:27], v[184:185]
	v_pk_add_f32 v[28:29], v[28:29], v[186:187]
	v_pk_mul_f32 v[150:151], v[30:31], v[30:31]
	v_pk_fma_f32 v[150:151], v[32:33], v[32:33], v[150:151]
	v_pk_fma_f32 v[150:151], v[26:27], v[26:27], v[150:151]
	v_pk_fma_f32 v[150:151], v[28:29], v[28:29], v[150:151]
	v_cvt_pk_bf16_f32 v180, v30, v31
	v_cvt_pk_bf16_f32 v181, v32, v33
	v_cvt_pk_bf16_f32 v182, v26, v27
	v_cvt_pk_bf16_f32 v183, v28, v29
	global_store_dwordx4 v179, v[180:183], s[44:45]
	v_pk_mul_f32 v[30:31], v[30:31], v[164:165]
	v_pk_mul_f32 v[32:33], v[32:33], v[166:167]
	v_pk_mul_f32 v[26:27], v[26:27], v[162:163]
	v_pk_mul_f32 v[28:29], v[28:29], v[176:177]
	v_cvt_pk_bf16_f32 v240, v30, v31
	v_cvt_pk_bf16_f32 v241, v32, v33
	v_cvt_pk_bf16_f32 v242, v26, v27
	v_cvt_pk_bf16_f32 v243, v28, v29
	global_store_dwordx4 v179, v[240:243], s[46:47]
	v_pk_add_f32 v[22:23], v[22:23], v[188:189]
	v_pk_add_f32 v[24:25], v[24:25], v[190:191]
	v_pk_add_f32 v[18:19], v[18:19], v[192:193]
	v_pk_add_f32 v[20:21], v[20:21], v[194:195]
	v_pk_mul_f32 v[152:153], v[22:23], v[22:23]
	v_pk_fma_f32 v[152:153], v[24:25], v[24:25], v[152:153]
	v_pk_fma_f32 v[152:153], v[18:19], v[18:19], v[152:153]
	v_pk_fma_f32 v[152:153], v[20:21], v[20:21], v[152:153]
	v_cvt_pk_bf16_f32 v188, v22, v23
	v_cvt_pk_bf16_f32 v189, v24, v25
	v_cvt_pk_bf16_f32 v190, v18, v19
	v_cvt_pk_bf16_f32 v191, v20, v21
	global_store_dwordx4 v179, v[188:191], s[44:45] offset:256
	v_pk_mul_f32 v[22:23], v[22:23], v[156:157]
	v_pk_mul_f32 v[24:25], v[24:25], v[158:159]
	v_pk_mul_f32 v[18:19], v[18:19], v[154:155]
	v_pk_mul_f32 v[20:21], v[20:21], v[160:161]
	v_cvt_pk_bf16_f32 v244, v22, v23
	v_cvt_pk_bf16_f32 v245, v24, v25
	v_cvt_pk_bf16_f32 v246, v18, v19
	v_cvt_pk_bf16_f32 v247, v20, v21
	global_store_dwordx4 v179, v[244:247], s[46:47] offset:256
	v_pk_add_f32 v[150:151], v[150:151], v[152:153]
	v_add_f32_e32 v0, v150, v151
	s_waitcnt vmcnt(8)
	s_add_u32 s44, s48, 0x58000
	s_addc_u32 s45, s49, 0
	s_add_u32 s46, s80, 0x58000
	s_addc_u32 s47, s81, 0
	v_pk_add_f32 v[14:15], v[14:15], v[196:197]
	v_pk_add_f32 v[16:17], v[16:17], v[198:199]
	v_pk_add_f32 v[10:11], v[10:11], v[200:201]
	v_pk_add_f32 v[12:13], v[12:13], v[202:203]
	v_pk_mul_f32 v[150:151], v[14:15], v[14:15]
	v_pk_fma_f32 v[150:151], v[16:17], v[16:17], v[150:151]
	v_pk_fma_f32 v[150:151], v[10:11], v[10:11], v[150:151]
	v_pk_fma_f32 v[150:151], v[12:13], v[12:13], v[150:151]
	v_cvt_pk_bf16_f32 v196, v14, v15
	v_cvt_pk_bf16_f32 v197, v16, v17
	v_cvt_pk_bf16_f32 v198, v10, v11
	v_cvt_pk_bf16_f32 v199, v12, v13
	global_store_dwordx4 v179, v[196:199], s[44:45]
	v_pk_mul_f32 v[14:15], v[14:15], v[164:165]
	v_pk_mul_f32 v[16:17], v[16:17], v[166:167]
	v_pk_mul_f32 v[10:11], v[10:11], v[162:163]
	v_pk_mul_f32 v[12:13], v[12:13], v[176:177]
	v_cvt_pk_bf16_f32 v240, v14, v15
	v_cvt_pk_bf16_f32 v241, v16, v17
	v_cvt_pk_bf16_f32 v242, v10, v11
	v_cvt_pk_bf16_f32 v243, v12, v13
	global_store_dwordx4 v179, v[240:243], s[46:47]
	v_pk_add_f32 v[6:7], v[6:7], v[204:205]
	v_pk_add_f32 v[8:9], v[8:9], v[206:207]
	v_pk_add_f32 v[2:3], v[2:3], v[236:237]
	v_pk_add_f32 v[4:5], v[4:5], v[238:239]
	v_pk_mul_f32 v[152:153], v[6:7], v[6:7]
	v_pk_fma_f32 v[152:153], v[8:9], v[8:9], v[152:153]
	v_pk_fma_f32 v[152:153], v[2:3], v[2:3], v[152:153]
	v_pk_fma_f32 v[152:153], v[4:5], v[4:5], v[152:153]
	v_cvt_pk_bf16_f32 v204, v6, v7
	v_cvt_pk_bf16_f32 v205, v8, v9
	v_cvt_pk_bf16_f32 v206, v2, v3
	v_cvt_pk_bf16_f32 v207, v4, v5
	global_store_dwordx4 v179, v[204:207], s[44:45] offset:256
	v_pk_mul_f32 v[6:7], v[6:7], v[156:157]
	v_pk_mul_f32 v[8:9], v[8:9], v[158:159]
	v_pk_mul_f32 v[2:3], v[2:3], v[154:155]
	v_pk_mul_f32 v[4:5], v[4:5], v[160:161]
	v_cvt_pk_bf16_f32 v244, v6, v7
	v_cvt_pk_bf16_f32 v245, v8, v9
	v_cvt_pk_bf16_f32 v246, v2, v3
	v_cvt_pk_bf16_f32 v247, v4, v5
	global_store_dwordx4 v179, v[244:247], s[46:47] offset:256
	v_pk_add_f32 v[150:151], v[150:151], v[152:153]
	v_add_f32_e32 v230, v150, v151
	s_branch .Lfo_tail
